# K_Q GEMM epilogue: one dwordx4 per row for the 12 sum-of-squares partials (lane group g takes 4, group 3 masked), all 8 rows at the top, cross-lane sum; 8 loads per wave instead of 24 and no vmcnt(0)
# baseline (speedup 1.0000x reference)
; __device__ __forceinline__ u32x4 pack8(const f32x4& a, const f32x4& b) { u32x4 w; w.x = cvt_pk_bf16(a[0], a[1]); w.y = cvt_pk_bf16(a[2], a[3]); w.z = cvt_pk_bf16(b[0], b[1]); w.w = cvt_pk_bf16(b[2], b[3]); return w; }
;     __device__ __forceinline__ void apply(const Ld& d, int row, int c0, int, int, int, const f32x4& a0, const f32x4& b0, const f32x4& a1, const f32x4& b1) const { half(d.g0, row, c0, a0, b0); half(d.g1, row, c0 + 128, a1, b1); }
;     __device__ __forceinline__ void apply(const Ld& d, int row, int c0, int, int, int, const f32x4& a0, const f32x4& b0, const f32x4& a1, const f32x4& b1) const { half(d.g0, d.p0, row, c0, a0, b0); half(d.g1, d.p1, row, c0 + 128, a1, b1); }
;     __device__ __forceinline__ void operator()(const f32x4 (&acc)[2][2][4][2], const Unit& u, int wr, int wc, int fr, int fq) const {
;         const int c0 = u.pn * BM + wc * 32 + 8 * fq;
; #pragma unroll
;         for (int ai = 0; ai < 2; ++ai)
; #pragma unroll
;             for (int mp = 0; mp < 4; mp += 2) {
;                 typename F::Ld ld[2];
; #pragma unroll
;                 for (int m = 0; m < 2; ++m) f.load(ld[m], u.pm * BM + ai * HALF + wr * 64 + (mp + m) * 16 + fr, c0, u.pn, fq);
; #pragma unroll
;                 for (int m = 0; m < 2; ++m) f.apply(ld[m], u.pm * BM + ai * HALF + wr * 64 + (mp + m) * 16 + fr, c0, u.pn, wc, fq, acc[ai][0][mp + m][0], acc[ai][0][mp + m][1], acc[ai][1][mp + m][0], acc[ai][1][mp + m][1]);
;     __device__ __forceinline__ void load(Ld& d, int row, int, int, int) const {
; #pragma unroll
;         for (int i = 0; i < 3; ++i) d.p[i] = ((const f32x4*)(ssqq + (size_t)row * 12))[i]; }
;     __device__ __forceinline__ void apply(const Ld& d, int row, int c0, int, int, int, const f32x4& a0, const f32x4& b0, const f32x4& a1, const f32x4& b1) const {
;         const f32x4 t = d.p[0] + d.p[1] + d.p[2];
;         const float inv = __builtin_amdgcn_rsqf(((t[0] + t[1]) + (t[2] + t[3])) * (1.f / 768.f) + EPS);
;         *(u32x4*)(o + (size_t)row * 768 + c0) = pack8(a0 * inv, b0 * inv); *(u32x4*)(o + (size_t)row * 768 + c0 + 128) = pack8(a1 * inv, b1 * inv); }
.LBB0_292:
	s_andn2_b64 vcc, exec, s[0:1]
	s_cbranch_vccnz .LBB0_294
	v_lshl_or_b32 v134, s71, 8, v241
	v_readlane_b32 s0, v254, 62
	v_ashrrev_i32_e32 v135, 31, v134
	v_readlane_b32 s1, v254, 63
	s_nop 1
	v_lshl_add_u64 v[154:155], v[134:135], 1, s[0:1]
	s_lshl_b32 s0, s63, 8
	v_add_u32_e32 v0, s0, v17
	v_and_b32_e32 v183, 0x30, v228
	v_min_u32_e32 v185, 32, v183
	v_mad_i64_i32 v[180:181], s[50:51], v0, 48, s[6:7]
	v_add_co_u32_e32 v180, vcc, v180, v185
	s_nop 1
	v_addc_co_u32_e32 v181, vcc, 0, v181, vcc
	s_movk_i32 s50, 0x1800
	s_mov_b32 s51, 0
	v_lshl_add_u64 v[230:231], v[180:181], 0, s[50:51]
	global_load_dwordx4 v[204:207], v[180:181], off
	global_load_dwordx4 v[208:211], v[180:181], off offset:768
	global_load_dwordx4 v[212:215], v[180:181], off offset:1536
	global_load_dwordx4 v[216:219], v[180:181], off offset:2304
	global_load_dwordx4 v[220:223], v[230:231], off
	global_load_dwordx4 v[224:227], v[230:231], off offset:768
	global_load_dwordx4 v[244:247], v[230:231], off offset:1536
	global_load_dwordx4 v[248:251], v[230:231], off offset:2304
	v_cmp_ne_u32_e32 vcc, 48, v183
	s_waitcnt vmcnt(7)
	v_add_f32_e32 v161, v204, v205
	v_add_f32_e32 v204, v206, v207
	s_waitcnt vmcnt(6)
	v_add_f32_e32 v162, v208, v209
	v_add_f32_e32 v208, v210, v211
	s_waitcnt vmcnt(5)
	v_add_f32_e32 v163, v212, v213
	v_add_f32_e32 v212, v214, v215
	s_waitcnt vmcnt(4)
	v_add_f32_e32 v164, v216, v217
	v_add_f32_e32 v216, v218, v219
	s_waitcnt vmcnt(3)
	v_add_f32_e32 v165, v220, v221
	v_add_f32_e32 v220, v222, v223
	s_waitcnt vmcnt(2)
	v_add_f32_e32 v166, v224, v225
	v_add_f32_e32 v224, v226, v227
	s_waitcnt vmcnt(1)
	v_add_f32_e32 v167, v244, v245
	v_add_f32_e32 v244, v246, v247
	s_waitcnt vmcnt(0)
	v_add_f32_e32 v168, v248, v249
	v_add_f32_e32 v248, v250, v251
	v_add_f32_e32 v161, v161, v204
	v_add_f32_e32 v162, v162, v208
	v_add_f32_e32 v163, v163, v212
	v_add_f32_e32 v164, v164, v216
	v_add_f32_e32 v165, v165, v220
	v_add_f32_e32 v166, v166, v224
	v_add_f32_e32 v167, v167, v244
	v_add_f32_e32 v168, v168, v248
	v_cndmask_b32_e32 v161, 0, v161, vcc
	v_cndmask_b32_e32 v162, 0, v162, vcc
	v_cndmask_b32_e32 v163, 0, v163, vcc
	v_cndmask_b32_e32 v164, 0, v164, vcc
	v_cndmask_b32_e32 v165, 0, v165, vcc
	v_cndmask_b32_e32 v166, 0, v166, vcc
	v_cndmask_b32_e32 v167, 0, v167, vcc
	v_cndmask_b32_e32 v168, 0, v168, vcc
	ds_swizzle_b32 v204, v161 offset:swizzle(SWAP,16)
	ds_swizzle_b32 v208, v162 offset:swizzle(SWAP,16)
	ds_swizzle_b32 v212, v163 offset:swizzle(SWAP,16)
	ds_swizzle_b32 v216, v164 offset:swizzle(SWAP,16)
	ds_swizzle_b32 v220, v165 offset:swizzle(SWAP,16)
	ds_swizzle_b32 v224, v166 offset:swizzle(SWAP,16)
	ds_swizzle_b32 v244, v167 offset:swizzle(SWAP,16)
	ds_swizzle_b32 v248, v168 offset:swizzle(SWAP,16)
	s_waitcnt lgkmcnt(0)
	v_add_f32_e32 v161, v161, v204
	v_add_f32_e32 v162, v162, v208
	v_add_f32_e32 v163, v163, v212
	v_add_f32_e32 v164, v164, v216
	v_add_f32_e32 v165, v165, v220
	v_add_f32_e32 v166, v166, v224
	v_add_f32_e32 v167, v167, v244
	v_add_f32_e32 v168, v168, v248
	v_mov_b32_e32 v204, v161
	v_mov_b32_e32 v208, v162
	v_mov_b32_e32 v212, v163
	v_mov_b32_e32 v216, v164
	v_mov_b32_e32 v220, v165
	v_mov_b32_e32 v224, v166
	v_mov_b32_e32 v244, v167
	v_mov_b32_e32 v248, v168
	s_nop 1
	v_permlane32_swap_b32_e32 v161, v204
	v_permlane32_swap_b32_e32 v162, v208
	v_permlane32_swap_b32_e32 v163, v212
	v_permlane32_swap_b32_e32 v164, v216
	v_permlane32_swap_b32_e32 v165, v220
	v_permlane32_swap_b32_e32 v166, v224
	v_permlane32_swap_b32_e32 v167, v244
	v_permlane32_swap_b32_e32 v168, v248
	v_add_f32_e32 v172, v161, v204
	v_add_f32_e32 v173, v162, v208
	v_add_f32_e32 v174, v163, v212
	v_add_f32_e32 v175, v164, v216
	v_add_f32_e32 v176, v165, v220
	v_add_f32_e32 v177, v166, v224
	v_add_f32_e32 v178, v167, v244
	v_add_f32_e32 v179, v168, v248
	v_fmamk_f32 v172, v172, 0x3aaaaaab, v229
	v_fmamk_f32 v173, v173, 0x3aaaaaab, v229
	v_fmamk_f32 v174, v174, 0x3aaaaaab, v229
	v_fmamk_f32 v175, v175, 0x3aaaaaab, v229
	v_fmamk_f32 v176, v176, 0x3aaaaaab, v229
	v_fmamk_f32 v177, v177, 0x3aaaaaab, v229
	v_fmamk_f32 v178, v178, 0x3aaaaaab, v229
	v_fmamk_f32 v179, v179, 0x3aaaaaab, v229
	v_rsq_f32_e32 v172, v172
	v_rsq_f32_e32 v173, v173
	v_rsq_f32_e32 v174, v174
	v_rsq_f32_e32 v175, v175
	v_rsq_f32_e32 v176, v176
	v_rsq_f32_e32 v177, v177
	v_rsq_f32_e32 v178, v178
	v_rsq_f32_e32 v179, v179
	s_nop 0
	s_nop 0
	s_movk_i32 s1, 0x600
	v_add_u32_e32 v160, s0, v236
	v_add_u32_e32 v144, s0, v235
	s_nop 0
	v_mov_b32_e32 v138, v172
	s_nop 0
	v_pk_mul_f32 v[136:137], v[132:133], v[138:139] op_sel_hi:[1,0]
	v_pk_mul_f32 v[134:135], v[130:131], v[138:139] op_sel_hi:[1,0]
	v_pk_mul_f32 v[140:141], v[128:129], v[138:139] op_sel_hi:[1,0]
	v_pk_mul_f32 v[142:143], v[126:127], v[138:139] op_sel_hi:[1,0]
	v_cvt_pk_bf16_f32 v134, v134, v135
	v_cvt_pk_bf16_f32 v135, v136, v137
	s_nop 0
	v_cvt_pk_bf16_f32 v136, v142, v143
	v_cvt_pk_bf16_f32 v137, v140, v141
	v_mad_i64_i32 v[140:141], s[22:23], v0, s1, v[154:155]
	global_store_dwordx4 v[140:141], v[134:137], off
	v_pk_mul_f32 v[142:143], v[120:121], v[138:139] op_sel_hi:[1,0]
	s_nop 0
	v_pk_mul_f32 v[136:137], v[124:125], v[138:139] op_sel_hi:[1,0]
	v_pk_mul_f32 v[134:135], v[122:123], v[138:139] op_sel_hi:[1,0]
	v_pk_mul_f32 v[138:139], v[118:119], v[138:139] op_sel_hi:[1,0]
	v_cvt_pk_bf16_f32 v134, v134, v135
	v_cvt_pk_bf16_f32 v135, v136, v137
	s_nop 0
	v_cvt_pk_bf16_f32 v136, v138, v139
	v_cvt_pk_bf16_f32 v137, v142, v143
	global_store_dwordx4 v[140:141], v[134:137], off offset:256
	s_nop 1
	s_nop 0
	s_nop 0
	v_mov_b32_e32 v138, v173
	s_nop 0
	v_pk_mul_f32 v[136:137], v[116:117], v[138:139] op_sel_hi:[1,0]
; __device__ __forceinline__ u32x4 pack8(const f32x4& a, const f32x4& b) { u32x4 w; w.x = cvt_pk_bf16(a[0], a[1]); w.y = cvt_pk_bf16(a[2], a[3]); w.z = cvt_pk_bf16(b[0], b[1]); w.w = cvt_pk_bf16(b[2], b[3]); return w; }
;     __device__ __forceinline__ void apply(const Ld& d, int row, int c0, int, int, int, const f32x4& a0, const f32x4& b0, const f32x4& a1, const f32x4& b1) const { half(d.g0, row, c0, a0, b0); half(d.g1, row, c0 + 128, a1, b1); }
;     __device__ __forceinline__ void apply(const Ld& d, int row, int c0, int, int, int, const f32x4& a0, const f32x4& b0, const f32x4& a1, const f32x4& b1) const { half(d.g0, d.p0, row, c0, a0, b0); half(d.g1, d.p1, row, c0 + 128, a1, b1); }
;     __device__ __forceinline__ void apply(const Ld& d, int row, int c0, int, int, int, const f32x4& a0, const f32x4& b0, const f32x4& a1, const f32x4& b1) const {
;         const f32x4 t = d.p[0] + d.p[1] + d.p[2];
;         const float inv = __builtin_amdgcn_rsqf(((t[0] + t[1]) + (t[2] + t[3])) * (1.f / 768.f) + EPS);
;         *(u32x4*)(o + (size_t)row * 768 + c0) = pack8(a0 * inv, b0 * inv); *(u32x4*)(o + (size_t)row * 768 + c0 + 128) = pack8(a1 * inv, b1 * inv); }
	v_pk_mul_f32 v[134:135], v[114:115], v[138:139] op_sel_hi:[1,0]
	v_pk_mul_f32 v[140:141], v[112:113], v[138:139] op_sel_hi:[1,0]
	v_pk_mul_f32 v[142:143], v[110:111], v[138:139] op_sel_hi:[1,0]
	v_cvt_pk_bf16_f32 v134, v134, v135
	v_cvt_pk_bf16_f32 v135, v136, v137
	s_nop 0
	v_cvt_pk_bf16_f32 v136, v142, v143
	v_cvt_pk_bf16_f32 v137, v140, v141
	v_mad_i64_i32 v[140:141], s[22:23], v144, s1, v[154:155]
	global_store_dwordx4 v[140:141], v[134:137], off
	v_pk_mul_f32 v[142:143], v[104:105], v[138:139] op_sel_hi:[1,0]
	s_nop 0
	v_pk_mul_f32 v[134:135], v[106:107], v[138:139] op_sel_hi:[1,0]
	v_pk_mul_f32 v[136:137], v[108:109], v[138:139] op_sel_hi:[1,0]
	v_cvt_pk_bf16_f32 v134, v134, v135
	v_pk_mul_f32 v[138:139], v[102:103], v[138:139] op_sel_hi:[1,0]
	v_cvt_pk_bf16_f32 v135, v136, v137
	s_nop 0
	v_cvt_pk_bf16_f32 v136, v138, v139
	v_cvt_pk_bf16_f32 v137, v142, v143
	global_store_dwordx4 v[140:141], v[134:137], off offset:256
	s_nop 1
	s_nop 0
	v_mov_b32_e32 v146, v174
	v_pk_mul_f32 v[144:145], v[100:101], v[146:147] op_sel_hi:[1,0]
	v_pk_mul_f32 v[142:143], v[98:99], v[146:147] op_sel_hi:[1,0]
	v_pk_mul_f32 v[148:149], v[96:97], v[146:147] op_sel_hi:[1,0]
	v_mov_b32_e32 v138, v175
	v_pk_mul_f32 v[150:151], v[94:95], v[146:147] op_sel_hi:[1,0]
	v_cvt_pk_bf16_f32 v142, v142, v143
	v_cvt_pk_bf16_f32 v143, v144, v145
	v_pk_mul_f32 v[136:137], v[84:85], v[138:139] op_sel_hi:[1,0]
	v_cvt_pk_bf16_f32 v144, v150, v151
	v_cvt_pk_bf16_f32 v145, v148, v149
	v_mad_i64_i32 v[148:149], s[22:23], v160, s1, v[154:155]
	global_store_dwordx4 v[148:149], v[142:145], off
	v_pk_mul_f32 v[150:151], v[88:89], v[146:147] op_sel_hi:[1,0]
	v_pk_mul_f32 v[134:135], v[82:83], v[138:139] op_sel_hi:[1,0]
	v_pk_mul_f32 v[144:145], v[92:93], v[146:147] op_sel_hi:[1,0]
	v_pk_mul_f32 v[142:143], v[90:91], v[146:147] op_sel_hi:[1,0]
	v_pk_mul_f32 v[146:147], v[86:87], v[146:147] op_sel_hi:[1,0]
	v_cvt_pk_bf16_f32 v142, v142, v143
	v_cvt_pk_bf16_f32 v143, v144, v145
	v_pk_mul_f32 v[140:141], v[80:81], v[138:139] op_sel_hi:[1,0]
	v_cvt_pk_bf16_f32 v144, v146, v147
	v_cvt_pk_bf16_f32 v145, v150, v151
	global_store_dwordx4 v[148:149], v[142:145], off offset:256
	v_cvt_pk_bf16_f32 v134, v134, v135
	v_cvt_pk_bf16_f32 v135, v136, v137
	v_add_u32_e32 v160, 0x80, v0
	s_nop 0
	v_add_u32_e32 v144, s0, v237
	v_pk_mul_f32 v[142:143], v[78:79], v[138:139] op_sel_hi:[1,0]
	s_nop 0
	v_cvt_pk_bf16_f32 v136, v142, v143
	v_cvt_pk_bf16_f32 v137, v140, v141
	v_mad_i64_i32 v[140:141], s[22:23], v144, s1, v[154:155]
	global_store_dwordx4 v[140:141], v[134:137], off
	v_pk_mul_f32 v[142:143], v[72:73], v[138:139] op_sel_hi:[1,0]
	s_nop 0
	v_pk_mul_f32 v[134:135], v[74:75], v[138:139] op_sel_hi:[1,0]
	v_pk_mul_f32 v[136:137], v[76:77], v[138:139] op_sel_hi:[1,0]
	v_cvt_pk_bf16_f32 v134, v134, v135
	v_pk_mul_f32 v[138:139], v[70:71], v[138:139] op_sel_hi:[1,0]
	v_cvt_pk_bf16_f32 v135, v136, v137
	s_nop 0
	v_cvt_pk_bf16_f32 v136, v138, v139
	v_cvt_pk_bf16_f32 v137, v142, v143
	global_store_dwordx4 v[140:141], v[134:137], off offset:256
	s_nop 1
	s_nop 0
	v_mov_b32_e32 v146, v176
	v_pk_mul_f32 v[144:145], v[68:69], v[146:147] op_sel_hi:[1,0]
	v_pk_mul_f32 v[142:143], v[66:67], v[146:147] op_sel_hi:[1,0]
	v_pk_mul_f32 v[148:149], v[64:65], v[146:147] op_sel_hi:[1,0]
	v_mov_b32_e32 v138, v177
	v_pk_mul_f32 v[150:151], v[62:63], v[146:147] op_sel_hi:[1,0]
	v_cvt_pk_bf16_f32 v142, v142, v143
	v_cvt_pk_bf16_f32 v143, v144, v145
	v_pk_mul_f32 v[136:137], v[52:53], v[138:139] op_sel_hi:[1,0]
	v_cvt_pk_bf16_f32 v144, v150, v151
; __device__ __forceinline__ u32x4 pack8(const f32x4& a, const f32x4& b) { u32x4 w; w.x = cvt_pk_bf16(a[0], a[1]); w.y = cvt_pk_bf16(a[2], a[3]); w.z = cvt_pk_bf16(b[0], b[1]); w.w = cvt_pk_bf16(b[2], b[3]); return w; }
;     __device__ __forceinline__ void apply(const Ld& d, int row, int c0, int, int, int, const f32x4& a0, const f32x4& b0, const f32x4& a1, const f32x4& b1) const { half(d.g0, row, c0, a0, b0); half(d.g1, row, c0 + 128, a1, b1); }
;     __device__ __forceinline__ void apply(const Ld& d, int row, int c0, int, int, int, const f32x4& a0, const f32x4& b0, const f32x4& a1, const f32x4& b1) const { half(d.g0, d.p0, row, c0, a0, b0); half(d.g1, d.p1, row, c0 + 128, a1, b1); }
;     __device__ __forceinline__ void apply(const Ld& d, int row, int c0, int, int, int, const f32x4& a0, const f32x4& b0, const f32x4& a1, const f32x4& b1) const {
;         const f32x4 t = d.p[0] + d.p[1] + d.p[2];
;         const float inv = __builtin_amdgcn_rsqf(((t[0] + t[1]) + (t[2] + t[3])) * (1.f / 768.f) + EPS);
;         *(u32x4*)(o + (size_t)row * 768 + c0) = pack8(a0 * inv, b0 * inv); *(u32x4*)(o + (size_t)row * 768 + c0 + 128) = pack8(a1 * inv, b1 * inv); }
	v_cvt_pk_bf16_f32 v145, v148, v149
	v_mad_i64_i32 v[148:149], s[22:23], v160, s1, v[154:155]
	global_store_dwordx4 v[148:149], v[142:145], off
	v_pk_mul_f32 v[150:151], v[56:57], v[146:147] op_sel_hi:[1,0]
	v_pk_mul_f32 v[134:135], v[50:51], v[138:139] op_sel_hi:[1,0]
	v_pk_mul_f32 v[144:145], v[60:61], v[146:147] op_sel_hi:[1,0]
	v_pk_mul_f32 v[142:143], v[58:59], v[146:147] op_sel_hi:[1,0]
	v_pk_mul_f32 v[146:147], v[54:55], v[146:147] op_sel_hi:[1,0]
	v_cvt_pk_bf16_f32 v142, v142, v143
	v_cvt_pk_bf16_f32 v143, v144, v145
	v_pk_mul_f32 v[140:141], v[48:49], v[138:139] op_sel_hi:[1,0]
	v_cvt_pk_bf16_f32 v144, v146, v147
	v_cvt_pk_bf16_f32 v145, v150, v151
	global_store_dwordx4 v[148:149], v[142:145], off offset:256
	v_cvt_pk_bf16_f32 v134, v134, v135
	v_cvt_pk_bf16_f32 v135, v136, v137
	v_add_u32_e32 v160, s0, v239
	s_nop 0
	v_add_u32_e32 v144, s0, v238
	v_pk_mul_f32 v[142:143], v[46:47], v[138:139] op_sel_hi:[1,0]
	s_nop 0
	v_cvt_pk_bf16_f32 v136, v142, v143
	v_cvt_pk_bf16_f32 v137, v140, v141
	v_mad_i64_i32 v[140:141], s[22:23], v144, s1, v[154:155]
	global_store_dwordx4 v[140:141], v[134:137], off
	v_pk_mul_f32 v[142:143], v[40:41], v[138:139] op_sel_hi:[1,0]
	s_nop 0
	v_pk_mul_f32 v[134:135], v[42:43], v[138:139] op_sel_hi:[1,0]
	v_pk_mul_f32 v[136:137], v[44:45], v[138:139] op_sel_hi:[1,0]
	v_cvt_pk_bf16_f32 v134, v134, v135
	v_pk_mul_f32 v[138:139], v[38:39], v[138:139] op_sel_hi:[1,0]
	v_cvt_pk_bf16_f32 v135, v136, v137
	s_nop 0
	v_cvt_pk_bf16_f32 v136, v138, v139
	v_cvt_pk_bf16_f32 v137, v142, v143
	global_store_dwordx4 v[140:141], v[134:137], off offset:256
	s_nop 1
	s_nop 0
	v_mov_b32_e32 v0, v178
	v_pk_mul_f32 v[144:145], v[36:37], v[0:1] op_sel_hi:[1,0]
	v_pk_mul_f32 v[142:143], v[34:35], v[0:1] op_sel_hi:[1,0]
	v_pk_mul_f32 v[146:147], v[32:33], v[0:1] op_sel_hi:[1,0]
	v_pk_mul_f32 v[148:149], v[30:31], v[0:1] op_sel_hi:[1,0]
	v_cvt_pk_bf16_f32 v142, v142, v143
	v_cvt_pk_bf16_f32 v143, v144, v145
	v_cvt_pk_bf16_f32 v144, v148, v149
	v_cvt_pk_bf16_f32 v145, v146, v147
	v_mad_i64_i32 v[146:147], s[22:23], v160, s1, v[154:155]
	global_store_dwordx4 v[146:147], v[142:145], off
	v_pk_mul_f32 v[148:149], v[24:25], v[0:1] op_sel_hi:[1,0]
	v_pk_mul_f32 v[150:151], v[22:23], v[0:1] op_sel_hi:[1,0]
	v_pk_mul_f32 v[144:145], v[28:29], v[0:1] op_sel_hi:[1,0]
	v_pk_mul_f32 v[142:143], v[26:27], v[0:1] op_sel_hi:[1,0]
	v_mov_b32_e32 v0, v179
	v_cvt_pk_bf16_f32 v142, v142, v143
	v_cvt_pk_bf16_f32 v143, v144, v145
	v_cvt_pk_bf16_f32 v144, v150, v151
	v_cvt_pk_bf16_f32 v145, v148, v149
	global_store_dwordx4 v[146:147], v[142:145], off offset:256
	v_pk_mul_f32 v[136:137], v[20:21], v[0:1] op_sel_hi:[1,0]
	v_pk_mul_f32 v[134:135], v[18:19], v[0:1] op_sel_hi:[1,0]
	v_add_u32_e32 v142, s0, v240
	v_pk_mul_f32 v[138:139], v[12:13], v[0:1] op_sel_hi:[1,0]
	v_pk_mul_f32 v[140:141], v[10:11], v[0:1] op_sel_hi:[1,0]
	v_cvt_pk_bf16_f32 v134, v134, v135
	v_cvt_pk_bf16_f32 v135, v136, v137
	s_nop 0
	v_cvt_pk_bf16_f32 v136, v140, v141
	v_cvt_pk_bf16_f32 v137, v138, v139
	v_mad_i64_i32 v[138:139], s[0:1], v142, s1, v[154:155]
	global_store_dwordx4 v[138:139], v[134:137], off
	v_pk_mul_f32 v[140:141], v[4:5], v[0:1] op_sel_hi:[1,0]
	v_pk_mul_f32 v[142:143], v[2:3], v[0:1] op_sel_hi:[1,0]
	v_pk_mul_f32 v[136:137], v[8:9], v[0:1] op_sel_hi:[1,0]
	v_pk_mul_f32 v[134:135], v[6:7], v[0:1] op_sel_hi:[1,0]
	s_nop 0
	v_cvt_pk_bf16_f32 v134, v134, v135
	v_cvt_pk_bf16_f32 v135, v136, v137
	v_cvt_pk_bf16_f32 v136, v142, v143
	v_cvt_pk_bf16_f32 v137, v140, v141
	global_store_dwordx4 v[138:139], v[134:137], off offset:256
